# P8 k-loop: pointer SALU of each phase hoisted into the preceding MFMA segment (load segments now only M0 + 2 DMA)
# speedup vs baseline: 1.0100x; 1.0100x over previous
.Lp8_nostage:
	v_add_u32_e32 v168, 0x18000, v236
	v_add_u32_e32 v169, 0x1c000, v236
	ds_read_b128 v[130:133], v240
	ds_read_b128 v[134:137], v240 offset:1024
	ds_read_b128 v[138:141], v240 offset:2048
	ds_read_b128 v[142:145], v240 offset:3072
	ds_read_b128 v[146:149], v241
	ds_read_b128 v[150:153], v241 offset:1024
	ds_read_b128 v[154:157], v241 offset:2048
	ds_read_b128 v[158:161], v241 offset:3072
	ds_read_b128 v[176:179], v241 offset:4096
	ds_read_b128 v[180:183], v241 offset:5120
	ds_read_b128 v[184:187], v241 offset:6144
	ds_read_b128 v[188:191], v241 offset:7168
	s_add_u32 s50, s48, 0xfff80080
	s_addc_u32 s51, s49, -1
	s_cmp_eq_u32 s80, s87
	s_cselect_b32 s53, s41, s51
	s_cselect_b32 s52, s47, s50
	s_cselect_b32 s51, s39, s75
	s_cselect_b32 s50, s73, s74
	s_add_i32 m0, s21, 0xc000
	s_nop 0
	global_load_lds_dwordx4 v166, s[48:49]
	s_add_i32 m0, s21, 0xe000
	s_nop 0
	global_load_lds_dwordx4 v170, s[48:49]
	s_waitcnt vmcnt(10)
	s_barrier
	s_waitcnt lgkmcnt(0)
	s_setprio 1
	v_mfma_f32_16x16x32_bf16 v[126:129], v[130:133], v[146:149], 0
	ds_read_b128 v[192:195], v242
	v_mfma_f32_16x16x32_bf16 v[122:125], v[138:141], v[146:149], 0
	v_mfma_f32_16x16x32_bf16 v[118:121], v[130:133], v[154:157], 0
	v_mfma_f32_16x16x32_bf16 v[114:117], v[138:141], v[154:157], 0
	v_mfma_f32_16x16x32_bf16 v[106:109], v[130:133], v[176:179], 0
	ds_read_b128 v[196:199], v242 offset:1024
	v_mfma_f32_16x16x32_bf16 v[98:101], v[138:141], v[176:179], 0
	v_mfma_f32_16x16x32_bf16 v[90:93], v[130:133], v[184:187], 0
	v_mfma_f32_16x16x32_bf16 v[82:85], v[138:141], v[184:187], 0
	v_mfma_f32_16x16x32_bf16 v[126:129], v[134:137], v[150:153], v[126:129]
	ds_read_b128 v[200:203], v242 offset:2048
	v_mfma_f32_16x16x32_bf16 v[122:125], v[142:145], v[150:153], v[122:125]
	s_add_i32 s81, s68, s56
	s_add_u32 s96, s50, 0x80
	s_addc_u32 s97, s51, 0
	v_mfma_f32_16x16x32_bf16 v[118:121], v[134:137], v[158:161], v[118:121]
	v_mfma_f32_16x16x32_bf16 v[114:117], v[142:145], v[158:161], v[114:117]
	v_mfma_f32_16x16x32_bf16 v[106:109], v[134:137], v[180:183], v[106:109]
	ds_read_b128 v[204:207], v242 offset:3072
	v_mfma_f32_16x16x32_bf16 v[98:101], v[142:145], v[180:183], v[98:101]
	v_mfma_f32_16x16x32_bf16 v[90:93], v[134:137], v[188:191], v[90:93]
	v_mfma_f32_16x16x32_bf16 v[82:85], v[142:145], v[188:191], v[82:85]
	s_setprio 0
	s_barrier
	s_mov_b32 m0, s81
	s_nop 0
	global_load_lds_dwordx4 v162, s[50:51]
	s_add_i32 m0, s81, 0x2000
	s_nop 0
	global_load_lds_dwordx4 v164, s[50:51]
	s_waitcnt vmcnt(10)
	s_barrier
	s_waitcnt lgkmcnt(0)
	s_setprio 1
	v_mfma_f32_16x16x32_bf16 v[110:113], v[192:195], v[146:149], 0
	ds_read_b128 v[208:211], v241 offset:16384
	v_mfma_f32_16x16x32_bf16 v[102:105], v[200:203], v[146:149], 0
	v_mfma_f32_16x16x32_bf16 v[94:97], v[192:195], v[154:157], 0
	ds_read_b128 v[212:215], v241 offset:17408
	v_mfma_f32_16x16x32_bf16 v[86:89], v[200:203], v[154:157], 0
	v_mfma_f32_16x16x32_bf16 v[78:81], v[192:195], v[176:179], 0
	ds_read_b128 v[216:219], v241 offset:18432
	v_mfma_f32_16x16x32_bf16 v[74:77], v[200:203], v[176:179], 0
	v_mfma_f32_16x16x32_bf16 v[70:73], v[192:195], v[184:187], 0
	ds_read_b128 v[220:223], v241 offset:19456
	v_mfma_f32_16x16x32_bf16 v[66:69], v[200:203], v[184:187], 0
	v_mfma_f32_16x16x32_bf16 v[110:113], v[196:199], v[150:153], v[110:113]
	ds_read_b128 v[224:227], v241 offset:20480
	v_mfma_f32_16x16x32_bf16 v[102:105], v[204:207], v[150:153], v[102:105]
	s_add_u32 s94, s52, 0x80
	s_addc_u32 s95, s53, 0
	v_mfma_f32_16x16x32_bf16 v[94:97], v[196:199], v[158:161], v[94:97]
	ds_read_b128 v[228:231], v241 offset:21504
	v_mfma_f32_16x16x32_bf16 v[86:89], v[204:207], v[158:161], v[86:89]
	v_mfma_f32_16x16x32_bf16 v[78:81], v[196:199], v[180:183], v[78:81]
	ds_read_b128 v[232:235], v241 offset:22528
	v_mfma_f32_16x16x32_bf16 v[74:77], v[204:207], v[180:183], v[74:77]
	v_mfma_f32_16x16x32_bf16 v[70:73], v[196:199], v[188:191], v[70:73]
	ds_read_b128 v[246:249], v241 offset:23552
	v_mfma_f32_16x16x32_bf16 v[66:69], v[204:207], v[188:191], v[66:69]
	s_setprio 0
	s_barrier
	s_mov_b32 m0, s21
	s_nop 0
	global_load_lds_dwordx4 v162, s[52:53]
	s_mov_b32 m0, s59
	s_nop 0
	global_load_lds_dwordx4 v164, s[52:53]
	s_waitcnt vmcnt(8)
	s_barrier
	s_waitcnt lgkmcnt(0)
	s_setprio 1
	v_mfma_f32_16x16x32_bf16 v[62:65], v[130:133], v[208:211], 0
	ds_read_b128 v[146:149], v241 offset:32768
	v_mfma_f32_16x16x32_bf16 v[58:61], v[138:141], v[208:211], 0
	v_mfma_f32_16x16x32_bf16 v[54:57], v[130:133], v[216:219], 0
	ds_read_b128 v[150:153], v241 offset:33792
	v_mfma_f32_16x16x32_bf16 v[50:53], v[138:141], v[216:219], 0
	v_mfma_f32_16x16x32_bf16 v[42:45], v[130:133], v[224:227], 0
	ds_read_b128 v[154:157], v241 offset:34816
	v_mfma_f32_16x16x32_bf16 v[34:37], v[138:141], v[224:227], 0
	v_mfma_f32_16x16x32_bf16 v[26:29], v[130:133], v[232:235], 0
	ds_read_b128 v[158:161], v241 offset:35840
	v_mfma_f32_16x16x32_bf16 v[18:21], v[138:141], v[232:235], 0
	v_mfma_f32_16x16x32_bf16 v[62:65], v[134:137], v[212:215], v[62:65]
	ds_read_b128 v[176:179], v241 offset:36864
	v_mfma_f32_16x16x32_bf16 v[58:61], v[142:145], v[212:215], v[58:61]
	s_add_u32 s82, s50, 0x80000
	s_addc_u32 s83, s51, 0
	s_add_i32 s81, s69, s56
	v_mfma_f32_16x16x32_bf16 v[54:57], v[134:137], v[220:223], v[54:57]
	ds_read_b128 v[180:183], v241 offset:37888
	v_mfma_f32_16x16x32_bf16 v[50:53], v[142:145], v[220:223], v[50:53]
	v_mfma_f32_16x16x32_bf16 v[42:45], v[134:137], v[228:231], v[42:45]
	ds_read_b128 v[184:187], v241 offset:38912
	v_mfma_f32_16x16x32_bf16 v[34:37], v[142:145], v[228:231], v[34:37]
	v_mfma_f32_16x16x32_bf16 v[26:29], v[134:137], v[246:249], v[26:29]
	ds_read_b128 v[188:191], v241 offset:39936
	v_mfma_f32_16x16x32_bf16 v[18:21], v[142:145], v[246:249], v[18:21]
	s_setprio 0
	s_barrier
	s_mov_b32 m0, s81
	s_nop 0
	global_load_lds_dwordx4 v162, s[82:83]
	s_add_i32 m0, s81, 0x2000
	s_nop 0
	global_load_lds_dwordx4 v164, s[82:83]
	s_waitcnt vmcnt(10)
	s_barrier
	s_waitcnt lgkmcnt(0)
	s_setprio 1
	v_mfma_f32_16x16x32_bf16 v[46:49], v[192:195], v[208:211], 0
	ds_read_b128 v[130:133], v168
	v_mfma_f32_16x16x32_bf16 v[38:41], v[200:203], v[208:211], 0
	v_mfma_f32_16x16x32_bf16 v[30:33], v[192:195], v[216:219], 0
	v_mfma_f32_16x16x32_bf16 v[22:25], v[200:203], v[216:219], 0
	v_mfma_f32_16x16x32_bf16 v[14:17], v[192:195], v[224:227], 0
	ds_read_b128 v[134:137], v168 offset:1024
	v_mfma_f32_16x16x32_bf16 v[10:13], v[200:203], v[224:227], 0
	v_mfma_f32_16x16x32_bf16 v[6:9], v[192:195], v[232:235], 0
	v_mfma_f32_16x16x32_bf16 v[2:5], v[200:203], v[232:235], 0
	v_mfma_f32_16x16x32_bf16 v[46:49], v[196:199], v[212:215], v[46:49]
	ds_read_b128 v[138:141], v168 offset:2048
	v_mfma_f32_16x16x32_bf16 v[38:41], v[204:207], v[212:215], v[38:41]
	s_add_i32 s81, 0, 0x18000
	s_add_u32 s52, s52, 0x80000
	s_addc_u32 s53, s53, 0
	v_mfma_f32_16x16x32_bf16 v[30:33], v[196:199], v[220:223], v[30:33]
	v_mfma_f32_16x16x32_bf16 v[22:25], v[204:207], v[220:223], v[22:25]
	v_mfma_f32_16x16x32_bf16 v[14:17], v[196:199], v[228:231], v[14:17]
	ds_read_b128 v[142:145], v168 offset:3072
	v_mfma_f32_16x16x32_bf16 v[10:13], v[204:207], v[228:231], v[10:13]
	v_mfma_f32_16x16x32_bf16 v[6:9], v[196:199], v[246:249], v[6:9]
	v_mfma_f32_16x16x32_bf16 v[2:5], v[204:207], v[246:249], v[2:5]
	s_setprio 0
	s_barrier
	s_mov_b32 m0, s60
	s_nop 0
	global_load_lds_dwordx4 v162, s[52:53]
	s_mov_b32 m0, s61
	s_nop 0
	global_load_lds_dwordx4 v164, s[52:53]
	s_waitcnt vmcnt(10)
	s_barrier
	s_waitcnt lgkmcnt(0)
	s_setprio 1
	v_mfma_f32_16x16x32_bf16 v[126:129], v[130:133], v[146:149], v[126:129]
	ds_read_b128 v[192:195], v169
	v_mfma_f32_16x16x32_bf16 v[122:125], v[138:141], v[146:149], v[122:125]
	v_mfma_f32_16x16x32_bf16 v[118:121], v[130:133], v[154:157], v[118:121]
	v_mfma_f32_16x16x32_bf16 v[114:117], v[138:141], v[154:157], v[114:117]
	v_mfma_f32_16x16x32_bf16 v[106:109], v[130:133], v[176:179], v[106:109]
	ds_read_b128 v[196:199], v169 offset:1024
	v_mfma_f32_16x16x32_bf16 v[98:101], v[138:141], v[176:179], v[98:101]
	v_mfma_f32_16x16x32_bf16 v[90:93], v[130:133], v[184:187], v[90:93]
	v_mfma_f32_16x16x32_bf16 v[82:85], v[138:141], v[184:187], v[82:85]
	v_mfma_f32_16x16x32_bf16 v[126:129], v[134:137], v[150:153], v[126:129]
	ds_read_b128 v[200:203], v169 offset:2048
	v_mfma_f32_16x16x32_bf16 v[122:125], v[142:145], v[150:153], v[122:125]
	s_add_i32 s84, 0, 0x1c000
	s_add_i32 s85, s81, s56
	v_mfma_f32_16x16x32_bf16 v[118:121], v[134:137], v[158:161], v[118:121]
	v_mfma_f32_16x16x32_bf16 v[114:117], v[142:145], v[158:161], v[114:117]
	v_mfma_f32_16x16x32_bf16 v[106:109], v[134:137], v[180:183], v[106:109]
	ds_read_b128 v[204:207], v169 offset:3072
	v_mfma_f32_16x16x32_bf16 v[98:101], v[142:145], v[180:183], v[98:101]
	v_mfma_f32_16x16x32_bf16 v[90:93], v[134:137], v[188:191], v[90:93]
	v_mfma_f32_16x16x32_bf16 v[82:85], v[142:145], v[188:191], v[82:85]
	s_setprio 0
	s_barrier
	s_mov_b32 m0, s85
	s_nop 0
	global_load_lds_dwordx4 v162, s[96:97]
	s_add_i32 m0, s85, 0x2000
	s_nop 0
	global_load_lds_dwordx4 v164, s[96:97]
	s_waitcnt vmcnt(10)
	s_barrier
	s_waitcnt lgkmcnt(0)
	s_setprio 1
	v_mfma_f32_16x16x32_bf16 v[110:113], v[192:195], v[146:149], v[110:113]
	ds_read_b128 v[208:211], v241 offset:49152
	v_mfma_f32_16x16x32_bf16 v[102:105], v[200:203], v[146:149], v[102:105]
	v_mfma_f32_16x16x32_bf16 v[94:97], v[192:195], v[154:157], v[94:97]
	ds_read_b128 v[212:215], v241 offset:50176
	v_mfma_f32_16x16x32_bf16 v[86:89], v[200:203], v[154:157], v[86:89]
	v_mfma_f32_16x16x32_bf16 v[78:81], v[192:195], v[176:179], v[78:81]
	ds_read_b128 v[216:219], v241 offset:51200
	v_mfma_f32_16x16x32_bf16 v[74:77], v[200:203], v[176:179], v[74:77]
	v_mfma_f32_16x16x32_bf16 v[70:73], v[192:195], v[184:187], v[70:73]
	ds_read_b128 v[220:223], v241 offset:52224
	v_mfma_f32_16x16x32_bf16 v[66:69], v[200:203], v[184:187], v[66:69]
	v_mfma_f32_16x16x32_bf16 v[110:113], v[196:199], v[150:153], v[110:113]
	ds_read_b128 v[224:227], v241 offset:53248
	v_mfma_f32_16x16x32_bf16 v[102:105], v[204:207], v[150:153], v[102:105]
	v_mfma_f32_16x16x32_bf16 v[94:97], v[196:199], v[158:161], v[94:97]
	ds_read_b128 v[228:231], v241 offset:54272
	v_mfma_f32_16x16x32_bf16 v[86:89], v[204:207], v[158:161], v[86:89]
	v_mfma_f32_16x16x32_bf16 v[78:81], v[196:199], v[180:183], v[78:81]
	ds_read_b128 v[232:235], v241 offset:55296
	v_mfma_f32_16x16x32_bf16 v[74:77], v[204:207], v[180:183], v[74:77]
	v_mfma_f32_16x16x32_bf16 v[70:73], v[196:199], v[188:191], v[70:73]
	ds_read_b128 v[246:249], v241 offset:56320
	v_mfma_f32_16x16x32_bf16 v[66:69], v[204:207], v[188:191], v[66:69]
	s_setprio 0
	s_barrier
	s_mov_b32 m0, s64
	s_nop 0
	global_load_lds_dwordx4 v162, s[94:95]
	s_mov_b32 m0, s65
	s_nop 0
	global_load_lds_dwordx4 v164, s[94:95]
	s_waitcnt vmcnt(8)
	s_barrier
	s_waitcnt lgkmcnt(0)
	s_setprio 1
	v_mfma_f32_16x16x32_bf16 v[62:65], v[130:133], v[208:211], v[62:65]
	ds_read_b128 v[146:149], v241
	v_mfma_f32_16x16x32_bf16 v[58:61], v[138:141], v[208:211], v[58:61]
	v_mfma_f32_16x16x32_bf16 v[54:57], v[130:133], v[216:219], v[54:57]
	ds_read_b128 v[150:153], v241 offset:1024
	v_mfma_f32_16x16x32_bf16 v[50:53], v[138:141], v[216:219], v[50:53]
	v_mfma_f32_16x16x32_bf16 v[42:45], v[130:133], v[224:227], v[42:45]
	ds_read_b128 v[154:157], v241 offset:2048
	v_mfma_f32_16x16x32_bf16 v[34:37], v[138:141], v[224:227], v[34:37]
	v_mfma_f32_16x16x32_bf16 v[26:29], v[130:133], v[232:235], v[26:29]
	ds_read_b128 v[158:161], v241 offset:3072
	v_mfma_f32_16x16x32_bf16 v[18:21], v[138:141], v[232:235], v[18:21]
	v_mfma_f32_16x16x32_bf16 v[62:65], v[134:137], v[212:215], v[62:65]
	ds_read_b128 v[176:179], v241 offset:4096
	v_mfma_f32_16x16x32_bf16 v[58:61], v[142:145], v[212:215], v[58:61]
	s_add_u32 s50, s50, 0x80080
	s_addc_u32 s51, s51, 0
	s_add_i32 s84, s84, s56
	v_mfma_f32_16x16x32_bf16 v[54:57], v[134:137], v[220:223], v[54:57]
	ds_read_b128 v[180:183], v241 offset:5120
	v_mfma_f32_16x16x32_bf16 v[50:53], v[142:145], v[220:223], v[50:53]
	v_mfma_f32_16x16x32_bf16 v[42:45], v[134:137], v[228:231], v[42:45]
	ds_read_b128 v[184:187], v241 offset:6144
	v_mfma_f32_16x16x32_bf16 v[34:37], v[142:145], v[228:231], v[34:37]
	v_mfma_f32_16x16x32_bf16 v[26:29], v[134:137], v[246:249], v[26:29]
	ds_read_b128 v[188:191], v241 offset:7168
	v_mfma_f32_16x16x32_bf16 v[18:21], v[142:145], v[246:249], v[18:21]
	s_setprio 0
	s_barrier
	s_mov_b32 m0, s84
	s_nop 0
	global_load_lds_dwordx4 v162, s[50:51]
	s_add_i32 m0, s84, 0x2000
	s_nop 0
	global_load_lds_dwordx4 v164, s[50:51]
	s_waitcnt vmcnt(10)
	s_barrier
	s_waitcnt lgkmcnt(0)
	s_setprio 1
	v_mfma_f32_16x16x32_bf16 v[46:49], v[192:195], v[208:211], v[46:49]
	ds_read_b128 v[130:133], v240
	v_mfma_f32_16x16x32_bf16 v[38:41], v[200:203], v[208:211], v[38:41]
	v_mfma_f32_16x16x32_bf16 v[30:33], v[192:195], v[216:219], v[30:33]
	v_mfma_f32_16x16x32_bf16 v[22:25], v[200:203], v[216:219], v[22:25]
	v_mfma_f32_16x16x32_bf16 v[14:17], v[192:195], v[224:227], v[14:17]
	ds_read_b128 v[134:137], v240 offset:1024
	v_mfma_f32_16x16x32_bf16 v[10:13], v[200:203], v[224:227], v[10:13]
	v_mfma_f32_16x16x32_bf16 v[6:9], v[192:195], v[232:235], v[6:9]
	v_mfma_f32_16x16x32_bf16 v[2:5], v[200:203], v[232:235], v[2:5]
	v_mfma_f32_16x16x32_bf16 v[46:49], v[196:199], v[212:215], v[46:49]
	ds_read_b128 v[138:141], v240 offset:2048
	v_mfma_f32_16x16x32_bf16 v[38:41], v[204:207], v[212:215], v[38:41]
	s_add_i32 s80, s80, 2
	s_add_u32 s48, s48, 0x100
	s_addc_u32 s49, s49, 0
	s_add_u32 s74, s74, 0x100
	s_addc_u32 s75, s75, 0
	s_add_u32 s50, s48, 0xfff80080
	s_addc_u32 s51, s49, -1
	s_cmp_eq_u32 s80, s87
	s_cselect_b32 s53, s41, s51
	s_cselect_b32 s52, s47, s50
	s_cselect_b32 s51, s39, s75
	s_cselect_b32 s50, s73, s74
	v_mfma_f32_16x16x32_bf16 v[30:33], v[196:199], v[220:223], v[30:33]
	v_mfma_f32_16x16x32_bf16 v[22:25], v[204:207], v[220:223], v[22:25]
	v_mfma_f32_16x16x32_bf16 v[14:17], v[196:199], v[228:231], v[14:17]
	ds_read_b128 v[142:145], v240 offset:3072
	v_mfma_f32_16x16x32_bf16 v[10:13], v[204:207], v[228:231], v[10:13]
	v_mfma_f32_16x16x32_bf16 v[6:9], v[196:199], v[246:249], v[6:9]
	v_mfma_f32_16x16x32_bf16 v[2:5], v[204:207], v[246:249], v[2:5]
	s_setprio 0
	s_cmp_gt_u32 s80, s87
	s_barrier
	s_cbranch_scc0 .LBB0_1098
	s_branch .Lp8_loop_exit
.LBB0_1098:
	s_add_i32 m0, s21, 0xc000
	s_nop 0
	global_load_lds_dwordx4 v166, s[48:49]
	s_add_i32 m0, s21, 0xe000
	s_nop 0
	global_load_lds_dwordx4 v170, s[48:49]
	s_waitcnt vmcnt(10)
	s_barrier
	s_waitcnt lgkmcnt(0)
	s_setprio 1
	v_mfma_f32_16x16x32_bf16 v[126:129], v[130:133], v[146:149], v[126:129]
	ds_read_b128 v[192:195], v242
	v_mfma_f32_16x16x32_bf16 v[122:125], v[138:141], v[146:149], v[122:125]
	v_mfma_f32_16x16x32_bf16 v[118:121], v[130:133], v[154:157], v[118:121]
	v_mfma_f32_16x16x32_bf16 v[114:117], v[138:141], v[154:157], v[114:117]
	v_mfma_f32_16x16x32_bf16 v[106:109], v[130:133], v[176:179], v[106:109]
	ds_read_b128 v[196:199], v242 offset:1024
	v_mfma_f32_16x16x32_bf16 v[98:101], v[138:141], v[176:179], v[98:101]
	v_mfma_f32_16x16x32_bf16 v[90:93], v[130:133], v[184:187], v[90:93]
	v_mfma_f32_16x16x32_bf16 v[82:85], v[138:141], v[184:187], v[82:85]
	v_mfma_f32_16x16x32_bf16 v[126:129], v[134:137], v[150:153], v[126:129]
	ds_read_b128 v[200:203], v242 offset:2048
	v_mfma_f32_16x16x32_bf16 v[122:125], v[142:145], v[150:153], v[122:125]
	s_add_i32 s81, s68, s56
	s_add_u32 s96, s50, 0x80
	s_addc_u32 s97, s51, 0
	v_mfma_f32_16x16x32_bf16 v[118:121], v[134:137], v[158:161], v[118:121]
	v_mfma_f32_16x16x32_bf16 v[114:117], v[142:145], v[158:161], v[114:117]
	v_mfma_f32_16x16x32_bf16 v[106:109], v[134:137], v[180:183], v[106:109]
	ds_read_b128 v[204:207], v242 offset:3072
	v_mfma_f32_16x16x32_bf16 v[98:101], v[142:145], v[180:183], v[98:101]
	v_mfma_f32_16x16x32_bf16 v[90:93], v[134:137], v[188:191], v[90:93]
	v_mfma_f32_16x16x32_bf16 v[82:85], v[142:145], v[188:191], v[82:85]
	s_setprio 0
	s_barrier
	s_mov_b32 m0, s81
	s_nop 0
	global_load_lds_dwordx4 v162, s[50:51]
	s_add_i32 m0, s81, 0x2000
	s_nop 0
	global_load_lds_dwordx4 v164, s[50:51]
	s_waitcnt vmcnt(10)
	s_barrier
	s_waitcnt lgkmcnt(0)
	s_setprio 1
	v_mfma_f32_16x16x32_bf16 v[110:113], v[192:195], v[146:149], v[110:113]
	ds_read_b128 v[208:211], v241 offset:16384
	v_mfma_f32_16x16x32_bf16 v[102:105], v[200:203], v[146:149], v[102:105]
	v_mfma_f32_16x16x32_bf16 v[94:97], v[192:195], v[154:157], v[94:97]
	ds_read_b128 v[212:215], v241 offset:17408
	v_mfma_f32_16x16x32_bf16 v[86:89], v[200:203], v[154:157], v[86:89]
	v_mfma_f32_16x16x32_bf16 v[78:81], v[192:195], v[176:179], v[78:81]
	ds_read_b128 v[216:219], v241 offset:18432
	v_mfma_f32_16x16x32_bf16 v[74:77], v[200:203], v[176:179], v[74:77]
	v_mfma_f32_16x16x32_bf16 v[70:73], v[192:195], v[184:187], v[70:73]
	ds_read_b128 v[220:223], v241 offset:19456
	v_mfma_f32_16x16x32_bf16 v[66:69], v[200:203], v[184:187], v[66:69]
	v_mfma_f32_16x16x32_bf16 v[110:113], v[196:199], v[150:153], v[110:113]
	ds_read_b128 v[224:227], v241 offset:20480
	v_mfma_f32_16x16x32_bf16 v[102:105], v[204:207], v[150:153], v[102:105]
	s_add_u32 s94, s52, 0x80
	s_addc_u32 s95, s53, 0
	v_mfma_f32_16x16x32_bf16 v[94:97], v[196:199], v[158:161], v[94:97]
	ds_read_b128 v[228:231], v241 offset:21504
	v_mfma_f32_16x16x32_bf16 v[86:89], v[204:207], v[158:161], v[86:89]
	v_mfma_f32_16x16x32_bf16 v[78:81], v[196:199], v[180:183], v[78:81]
	ds_read_b128 v[232:235], v241 offset:22528
	v_mfma_f32_16x16x32_bf16 v[74:77], v[204:207], v[180:183], v[74:77]
	v_mfma_f32_16x16x32_bf16 v[70:73], v[196:199], v[188:191], v[70:73]
	ds_read_b128 v[246:249], v241 offset:23552
	v_mfma_f32_16x16x32_bf16 v[66:69], v[204:207], v[188:191], v[66:69]
	s_setprio 0
	s_barrier
	s_mov_b32 m0, s21
	s_nop 0
	global_load_lds_dwordx4 v162, s[52:53]
	s_mov_b32 m0, s59
	s_nop 0
	global_load_lds_dwordx4 v164, s[52:53]
	s_waitcnt vmcnt(8)
	s_barrier
	s_waitcnt lgkmcnt(0)
	s_setprio 1
	v_mfma_f32_16x16x32_bf16 v[62:65], v[130:133], v[208:211], v[62:65]
	ds_read_b128 v[146:149], v241 offset:32768
	v_mfma_f32_16x16x32_bf16 v[58:61], v[138:141], v[208:211], v[58:61]
	v_mfma_f32_16x16x32_bf16 v[54:57], v[130:133], v[216:219], v[54:57]
	ds_read_b128 v[150:153], v241 offset:33792
	v_mfma_f32_16x16x32_bf16 v[50:53], v[138:141], v[216:219], v[50:53]
	v_mfma_f32_16x16x32_bf16 v[42:45], v[130:133], v[224:227], v[42:45]
	ds_read_b128 v[154:157], v241 offset:34816
	v_mfma_f32_16x16x32_bf16 v[34:37], v[138:141], v[224:227], v[34:37]
	v_mfma_f32_16x16x32_bf16 v[26:29], v[130:133], v[232:235], v[26:29]
	ds_read_b128 v[158:161], v241 offset:35840
	v_mfma_f32_16x16x32_bf16 v[18:21], v[138:141], v[232:235], v[18:21]
	v_mfma_f32_16x16x32_bf16 v[62:65], v[134:137], v[212:215], v[62:65]
	ds_read_b128 v[176:179], v241 offset:36864
	v_mfma_f32_16x16x32_bf16 v[58:61], v[142:145], v[212:215], v[58:61]
	s_add_u32 s82, s50, 0x80000
	s_addc_u32 s83, s51, 0
	s_add_i32 s81, s69, s56
	v_mfma_f32_16x16x32_bf16 v[54:57], v[134:137], v[220:223], v[54:57]
	ds_read_b128 v[180:183], v241 offset:37888
	v_mfma_f32_16x16x32_bf16 v[50:53], v[142:145], v[220:223], v[50:53]
	v_mfma_f32_16x16x32_bf16 v[42:45], v[134:137], v[228:231], v[42:45]
	ds_read_b128 v[184:187], v241 offset:38912
	v_mfma_f32_16x16x32_bf16 v[34:37], v[142:145], v[228:231], v[34:37]
	v_mfma_f32_16x16x32_bf16 v[26:29], v[134:137], v[246:249], v[26:29]
	ds_read_b128 v[188:191], v241 offset:39936
	v_mfma_f32_16x16x32_bf16 v[18:21], v[142:145], v[246:249], v[18:21]
	s_setprio 0
	s_barrier
	s_mov_b32 m0, s81
	s_nop 0
	global_load_lds_dwordx4 v162, s[82:83]
	s_add_i32 m0, s81, 0x2000
	s_nop 0
	global_load_lds_dwordx4 v164, s[82:83]
	s_waitcnt vmcnt(10)
	s_barrier
	s_waitcnt lgkmcnt(0)
	s_setprio 1
	v_mfma_f32_16x16x32_bf16 v[46:49], v[192:195], v[208:211], v[46:49]
	ds_read_b128 v[130:133], v168
	v_mfma_f32_16x16x32_bf16 v[38:41], v[200:203], v[208:211], v[38:41]
	v_mfma_f32_16x16x32_bf16 v[30:33], v[192:195], v[216:219], v[30:33]
	v_mfma_f32_16x16x32_bf16 v[22:25], v[200:203], v[216:219], v[22:25]
	v_mfma_f32_16x16x32_bf16 v[14:17], v[192:195], v[224:227], v[14:17]
	ds_read_b128 v[134:137], v168 offset:1024
	v_mfma_f32_16x16x32_bf16 v[10:13], v[200:203], v[224:227], v[10:13]
	v_mfma_f32_16x16x32_bf16 v[6:9], v[192:195], v[232:235], v[6:9]
	v_mfma_f32_16x16x32_bf16 v[2:5], v[200:203], v[232:235], v[2:5]
	v_mfma_f32_16x16x32_bf16 v[46:49], v[196:199], v[212:215], v[46:49]
	ds_read_b128 v[138:141], v168 offset:2048
	v_mfma_f32_16x16x32_bf16 v[38:41], v[204:207], v[212:215], v[38:41]
	s_add_i32 s81, 0, 0x18000
	s_add_u32 s52, s52, 0x80000
	s_addc_u32 s53, s53, 0
	v_mfma_f32_16x16x32_bf16 v[30:33], v[196:199], v[220:223], v[30:33]
	v_mfma_f32_16x16x32_bf16 v[22:25], v[204:207], v[220:223], v[22:25]
	v_mfma_f32_16x16x32_bf16 v[14:17], v[196:199], v[228:231], v[14:17]
	ds_read_b128 v[142:145], v168 offset:3072
	v_mfma_f32_16x16x32_bf16 v[10:13], v[204:207], v[228:231], v[10:13]
	v_mfma_f32_16x16x32_bf16 v[6:9], v[196:199], v[246:249], v[6:9]
	v_mfma_f32_16x16x32_bf16 v[2:5], v[204:207], v[246:249], v[2:5]
	s_setprio 0
	s_barrier
	s_mov_b32 m0, s60
	s_nop 0
	global_load_lds_dwordx4 v162, s[52:53]
	s_mov_b32 m0, s61
	s_nop 0
	global_load_lds_dwordx4 v164, s[52:53]
	s_waitcnt vmcnt(10)
	s_barrier
	s_waitcnt lgkmcnt(0)
	s_setprio 1
	v_mfma_f32_16x16x32_bf16 v[126:129], v[130:133], v[146:149], v[126:129]
	ds_read_b128 v[192:195], v169
	v_mfma_f32_16x16x32_bf16 v[122:125], v[138:141], v[146:149], v[122:125]
	v_mfma_f32_16x16x32_bf16 v[118:121], v[130:133], v[154:157], v[118:121]
	v_mfma_f32_16x16x32_bf16 v[114:117], v[138:141], v[154:157], v[114:117]
	v_mfma_f32_16x16x32_bf16 v[106:109], v[130:133], v[176:179], v[106:109]
	ds_read_b128 v[196:199], v169 offset:1024
	v_mfma_f32_16x16x32_bf16 v[98:101], v[138:141], v[176:179], v[98:101]
	v_mfma_f32_16x16x32_bf16 v[90:93], v[130:133], v[184:187], v[90:93]
	v_mfma_f32_16x16x32_bf16 v[82:85], v[138:141], v[184:187], v[82:85]
	v_mfma_f32_16x16x32_bf16 v[126:129], v[134:137], v[150:153], v[126:129]
	ds_read_b128 v[200:203], v169 offset:2048
	v_mfma_f32_16x16x32_bf16 v[122:125], v[142:145], v[150:153], v[122:125]
	s_add_i32 s84, 0, 0x1c000
	s_add_i32 s85, s81, s56
	v_mfma_f32_16x16x32_bf16 v[118:121], v[134:137], v[158:161], v[118:121]
	v_mfma_f32_16x16x32_bf16 v[114:117], v[142:145], v[158:161], v[114:117]
	v_mfma_f32_16x16x32_bf16 v[106:109], v[134:137], v[180:183], v[106:109]
	ds_read_b128 v[204:207], v169 offset:3072
	v_mfma_f32_16x16x32_bf16 v[98:101], v[142:145], v[180:183], v[98:101]
	v_mfma_f32_16x16x32_bf16 v[90:93], v[134:137], v[188:191], v[90:93]
	v_mfma_f32_16x16x32_bf16 v[82:85], v[142:145], v[188:191], v[82:85]
	s_setprio 0
	s_barrier
	s_mov_b32 m0, s85
	s_nop 0
	global_load_lds_dwordx4 v162, s[96:97]
	s_add_i32 m0, s85, 0x2000
	s_nop 0
	global_load_lds_dwordx4 v164, s[96:97]
	s_waitcnt vmcnt(10)
	s_barrier
	s_waitcnt lgkmcnt(0)
	s_setprio 1
	v_mfma_f32_16x16x32_bf16 v[110:113], v[192:195], v[146:149], v[110:113]
	ds_read_b128 v[208:211], v241 offset:49152
	v_mfma_f32_16x16x32_bf16 v[102:105], v[200:203], v[146:149], v[102:105]
	v_mfma_f32_16x16x32_bf16 v[94:97], v[192:195], v[154:157], v[94:97]
	ds_read_b128 v[212:215], v241 offset:50176
	v_mfma_f32_16x16x32_bf16 v[86:89], v[200:203], v[154:157], v[86:89]
	v_mfma_f32_16x16x32_bf16 v[78:81], v[192:195], v[176:179], v[78:81]
	ds_read_b128 v[216:219], v241 offset:51200
	v_mfma_f32_16x16x32_bf16 v[74:77], v[200:203], v[176:179], v[74:77]
	v_mfma_f32_16x16x32_bf16 v[70:73], v[192:195], v[184:187], v[70:73]
	ds_read_b128 v[220:223], v241 offset:52224
	v_mfma_f32_16x16x32_bf16 v[66:69], v[200:203], v[184:187], v[66:69]
	v_mfma_f32_16x16x32_bf16 v[110:113], v[196:199], v[150:153], v[110:113]
	ds_read_b128 v[224:227], v241 offset:53248
	v_mfma_f32_16x16x32_bf16 v[102:105], v[204:207], v[150:153], v[102:105]
	v_mfma_f32_16x16x32_bf16 v[94:97], v[196:199], v[158:161], v[94:97]
	ds_read_b128 v[228:231], v241 offset:54272
	v_mfma_f32_16x16x32_bf16 v[86:89], v[204:207], v[158:161], v[86:89]
	v_mfma_f32_16x16x32_bf16 v[78:81], v[196:199], v[180:183], v[78:81]
	ds_read_b128 v[232:235], v241 offset:55296
	v_mfma_f32_16x16x32_bf16 v[74:77], v[204:207], v[180:183], v[74:77]
	v_mfma_f32_16x16x32_bf16 v[70:73], v[196:199], v[188:191], v[70:73]
	ds_read_b128 v[246:249], v241 offset:56320
	v_mfma_f32_16x16x32_bf16 v[66:69], v[204:207], v[188:191], v[66:69]
	s_setprio 0
	s_barrier
	s_mov_b32 m0, s64
	s_nop 0
	global_load_lds_dwordx4 v162, s[94:95]
	s_mov_b32 m0, s65
	s_nop 0
	global_load_lds_dwordx4 v164, s[94:95]
	s_waitcnt vmcnt(8)
	s_barrier
	s_waitcnt lgkmcnt(0)
	s_setprio 1
	v_mfma_f32_16x16x32_bf16 v[62:65], v[130:133], v[208:211], v[62:65]
	ds_read_b128 v[146:149], v241
	v_mfma_f32_16x16x32_bf16 v[58:61], v[138:141], v[208:211], v[58:61]
	v_mfma_f32_16x16x32_bf16 v[54:57], v[130:133], v[216:219], v[54:57]
	ds_read_b128 v[150:153], v241 offset:1024
	v_mfma_f32_16x16x32_bf16 v[50:53], v[138:141], v[216:219], v[50:53]
	v_mfma_f32_16x16x32_bf16 v[42:45], v[130:133], v[224:227], v[42:45]
	ds_read_b128 v[154:157], v241 offset:2048
	v_mfma_f32_16x16x32_bf16 v[34:37], v[138:141], v[224:227], v[34:37]
	v_mfma_f32_16x16x32_bf16 v[26:29], v[130:133], v[232:235], v[26:29]
	ds_read_b128 v[158:161], v241 offset:3072
	v_mfma_f32_16x16x32_bf16 v[18:21], v[138:141], v[232:235], v[18:21]
	v_mfma_f32_16x16x32_bf16 v[62:65], v[134:137], v[212:215], v[62:65]
	ds_read_b128 v[176:179], v241 offset:4096
	v_mfma_f32_16x16x32_bf16 v[58:61], v[142:145], v[212:215], v[58:61]
	s_add_u32 s50, s50, 0x80080
	s_addc_u32 s51, s51, 0
	s_add_i32 s84, s84, s56
	v_mfma_f32_16x16x32_bf16 v[54:57], v[134:137], v[220:223], v[54:57]
	ds_read_b128 v[180:183], v241 offset:5120
	v_mfma_f32_16x16x32_bf16 v[50:53], v[142:145], v[220:223], v[50:53]
	v_mfma_f32_16x16x32_bf16 v[42:45], v[134:137], v[228:231], v[42:45]
	ds_read_b128 v[184:187], v241 offset:6144
	v_mfma_f32_16x16x32_bf16 v[34:37], v[142:145], v[228:231], v[34:37]
	v_mfma_f32_16x16x32_bf16 v[26:29], v[134:137], v[246:249], v[26:29]
	ds_read_b128 v[188:191], v241 offset:7168
	v_mfma_f32_16x16x32_bf16 v[18:21], v[142:145], v[246:249], v[18:21]
	s_setprio 0
	s_barrier
	s_mov_b32 m0, s84
	s_nop 0
	global_load_lds_dwordx4 v162, s[50:51]
	s_add_i32 m0, s84, 0x2000
	s_nop 0
	global_load_lds_dwordx4 v164, s[50:51]
	s_waitcnt vmcnt(10)
	s_barrier
	s_waitcnt lgkmcnt(0)
	s_setprio 1
	v_mfma_f32_16x16x32_bf16 v[46:49], v[192:195], v[208:211], v[46:49]
	ds_read_b128 v[130:133], v240
	v_mfma_f32_16x16x32_bf16 v[38:41], v[200:203], v[208:211], v[38:41]
	v_mfma_f32_16x16x32_bf16 v[30:33], v[192:195], v[216:219], v[30:33]
	v_mfma_f32_16x16x32_bf16 v[22:25], v[200:203], v[216:219], v[22:25]
	v_mfma_f32_16x16x32_bf16 v[14:17], v[192:195], v[224:227], v[14:17]
	ds_read_b128 v[134:137], v240 offset:1024
	v_mfma_f32_16x16x32_bf16 v[10:13], v[200:203], v[224:227], v[10:13]
	v_mfma_f32_16x16x32_bf16 v[6:9], v[192:195], v[232:235], v[6:9]
	v_mfma_f32_16x16x32_bf16 v[2:5], v[200:203], v[232:235], v[2:5]
	v_mfma_f32_16x16x32_bf16 v[46:49], v[196:199], v[212:215], v[46:49]
	ds_read_b128 v[138:141], v240 offset:2048
	v_mfma_f32_16x16x32_bf16 v[38:41], v[204:207], v[212:215], v[38:41]
	s_add_i32 s80, s80, 2
	s_add_u32 s48, s48, 0x100
	s_addc_u32 s49, s49, 0
	s_add_u32 s74, s74, 0x100
	s_addc_u32 s75, s75, 0
	s_add_u32 s50, s48, 0xfff80080
	s_addc_u32 s51, s49, -1
	s_cmp_eq_u32 s80, s87
	s_cselect_b32 s53, s41, s51
	s_cselect_b32 s52, s47, s50
	s_cselect_b32 s51, s39, s75
	s_cselect_b32 s50, s73, s74
	v_mfma_f32_16x16x32_bf16 v[30:33], v[196:199], v[220:223], v[30:33]
	v_mfma_f32_16x16x32_bf16 v[22:25], v[204:207], v[220:223], v[22:25]
	v_mfma_f32_16x16x32_bf16 v[14:17], v[196:199], v[228:231], v[14:17]
	ds_read_b128 v[142:145], v240 offset:3072
	v_mfma_f32_16x16x32_bf16 v[10:13], v[204:207], v[228:231], v[10:13]
	v_mfma_f32_16x16x32_bf16 v[6:9], v[196:199], v[246:249], v[6:9]
	v_mfma_f32_16x16x32_bf16 v[2:5], v[204:207], v[246:249], v[2:5]
	s_setprio 0
	s_cmp_gt_u32 s80, s87
	s_barrier
	s_cbranch_scc0 .LBB0_1098
